# spatial gating: layernorm gain/bias vectors of group g+1 prefetched during group g (no L2 round trip at the top of each group)
# baseline (speedup 1.0000x reference)
; #define LDSP(T, p) ((__attribute__((address_space(3))) T*)(p))
; DI unsigned pk2(float lo, float hi) { bf2_t v = __builtin_convertvector((f32x2){lo, hi}, bf2_t); return __builtin_bit_cast(unsigned, v); }
; DI float bf_lo(unsigned u) { return __uint_as_float(u << 16); }
; DI float bf_hi(unsigned u) { return __uint_as_float(u & 0xffff0000u); }
; DI void sg_phase(const Params& p, lds_t* shm) {
;     ...
;     u32x4 raw[4];
; #pragma unroll
;     for (int i = 0; i < 4; ++i) { const int idx = tid + 512 * i, row = idx >> 4, ch = idx & 15; raw[i] = *(const u32x4*)(Vs + (size_t)(w * 128 + row) * DM + ch * 8); }
;     for (int g = 0; g < 8; ++g) {
;       __syncthreads();
; #pragma unroll
;       for (int i = 0; i < 4; ++i) {
;         const int idx = tid + 512 * i, row = idx >> 4, ch = idx & 15; const int c0 = g * 128 + ch * 8;
;         const u32x4 v = raw[i];
;         const float mu = stats[2 * row], rs = stats[2 * row + 1];
;         const f32x4 g0 = *(const f32x4*)(p.ln_g + c0), g1 = *(const f32x4*)(p.ln_g + c0 + 4), b0 = *(const f32x4*)(p.ln_b + c0), b1 = *(const f32x4*)(p.ln_b + c0 + 4);
;         u32x4 o;
;         o.x = pk2((bf_lo(v.x) - mu) * rs * g0[0] + b0[0], (bf_hi(v.x) - mu) * rs * g0[1] + b0[1]);
;         o.y = pk2((bf_lo(v.y) - mu) * rs * g0[2] + b0[2], (bf_hi(v.y) - mu) * rs * g0[3] + b0[3]);
;         o.z = pk2((bf_lo(v.z) - mu) * rs * g1[0] + b1[0], (bf_hi(v.z) - mu) * rs * g1[1] + b1[1]);
;         o.w = pk2((bf_lo(v.w) - mu) * rs * g1[2] + b1[2], (bf_hi(v.w) - mu) * rs * g1[3] + b1[3]);
;         *LDSP(u32x4, shm + off_a(row, ch)) = o;
;       }
.LBB0_395:
	s_or_b64 exec, exec, s[0:1]
	v_add_u32_e32 v0, s8, v84
	v_ashrrev_i32_e32 v1, 31, v0
	s_waitcnt lgkmcnt(6)
	v_add_u32_e32 v2, s8, v85
	v_lshlrev_b64 v[58:59], 11, v[0:1]
	v_ashrrev_i32_e32 v3, 31, v2
	v_lshl_add_u64 v[0:1], v[52:53], 0, v[58:59]
	v_lshlrev_b64 v[60:61], 11, v[2:3]
	v_lshl_add_u64 v[2:3], v[52:53], 0, v[60:61]
	global_load_dwordx4 v[32:35], v[0:1], off
	global_load_dwordx4 v[36:39], v[2:3], off
	v_add_u32_e32 v0, s8, v86
	v_ashrrev_i32_e32 v1, 31, v0
	v_add_u32_e32 v2, s8, v87
	v_lshlrev_b64 v[62:63], 11, v[0:1]
	v_ashrrev_i32_e32 v3, 31, v2
	v_lshl_add_u64 v[0:1], v[52:53], 0, v[62:63]
	v_lshlrev_b64 v[64:65], 11, v[2:3]
	v_lshl_add_u64 v[2:3], v[52:53], 0, v[64:65]
	global_load_dwordx4 v[40:43], v[0:1], off
	global_load_dwordx4 v[44:47], v[2:3], off
	v_or_b32_e32 v0, s8, v79
	v_ashrrev_i32_e32 v1, 31, v0
	v_lshlrev_b64 v[0:1], 11, v[0:1]
	v_lshl_add_u64 v[66:67], v[56:57], 0, v[0:1]
	s_mov_b32 s0, 0
	s_mov_b32 s99, 0
	v_or_b32_e32 v234, s99, v77
	v_mov_b32_e32 v235, 0
	v_lshlrev_b64 v[234:235], 2, v[234:235]
	v_lshl_add_u64 v[236:237], s[40:41], 0, v[234:235]
	v_lshl_add_u64 v[234:235], s[42:43], 0, v[234:235]
	global_load_dwordx4 v[218:221], v[234:235], off
	global_load_dwordx4 v[222:225], v[236:237], off
	global_load_dwordx4 v[226:229], v[236:237], off offset:16
	global_load_dwordx4 v[230:233], v[234:235], off offset:16
.LBB0_396:
	s_lshl_b32 s1, s0, 7
	v_or_b32_e32 v48, s1, v77
	s_waitcnt lgkmcnt(2)
	s_waitcnt lgkmcnt(0)
	s_barrier
	s_nop 0
	s_nop 0
	ds_read_b64 v[16:17], v91 offset:32768
	s_waitcnt vmcnt(7)
	v_lshlrev_b32_e32 v18, 16, v32
	v_and_b32_e32 v19, 0xffff0000, v32
	v_lshlrev_b32_e32 v20, 16, v33
	v_and_b32_e32 v21, 0xffff0000, v33
	v_lshlrev_b32_e32 v22, 16, v34
	v_and_b32_e32 v23, 0xffff0000, v34
	v_lshlrev_b32_e32 v24, 16, v35
	v_and_b32_e32 v25, 0xffff0000, v35
	s_waitcnt lgkmcnt(0)
	v_pk_add_f32 v[18:19], v[18:19], v[16:17] op_sel_hi:[1,0] neg_lo:[0,1] neg_hi:[0,1]
	v_pk_add_f32 v[20:21], v[20:21], v[16:17] op_sel_hi:[1,0] neg_lo:[0,1] neg_hi:[0,1]
	v_pk_add_f32 v[22:23], v[22:23], v[16:17] op_sel_hi:[1,0] neg_lo:[0,1] neg_hi:[0,1]
	v_pk_add_f32 v[24:25], v[24:25], v[16:17] op_sel_hi:[1,0] neg_lo:[0,1] neg_hi:[0,1]
	v_pk_mul_f32 v[18:19], v[16:17], v[18:19] op_sel:[1,0]
	v_pk_mul_f32 v[20:21], v[16:17], v[20:21] op_sel:[1,0]
	v_pk_mul_f32 v[22:23], v[16:17], v[22:23] op_sel:[1,0]
	v_pk_mul_f32 v[16:17], v[16:17], v[24:25] op_sel:[1,0]
	s_waitcnt vmcnt(6)
	v_lshlrev_b32_e32 v26, 16, v36
	v_and_b32_e32 v27, 0xffff0000, v36
	v_lshlrev_b32_e32 v28, 16, v37
	v_and_b32_e32 v29, 0xffff0000, v37
	v_lshlrev_b32_e32 v30, 16, v38
	v_and_b32_e32 v31, 0xffff0000, v38
	v_lshlrev_b32_e32 v68, 16, v39
	v_and_b32_e32 v69, 0xffff0000, v39
	s_waitcnt vmcnt(5)
	v_lshlrev_b32_e32 v100, 16, v40
	v_and_b32_e32 v101, 0xffff0000, v40
	v_lshlrev_b32_e32 v102, 16, v41
	v_and_b32_e32 v103, 0xffff0000, v41
	v_lshlrev_b32_e32 v104, 16, v42
	v_and_b32_e32 v105, 0xffff0000, v42
	s_mov_b32 s4, s0
	s_add_i32 s0, s0, 1
	s_cmp_eq_u32 s4, 7
	s_waitcnt vmcnt(2)
	v_pk_fma_f32 v[18:19], v[18:19], v[222:223], v[218:219]
	v_pk_fma_f32 v[20:21], v[20:21], v[224:225], v[220:221]
	s_waitcnt vmcnt(0)
	v_pk_fma_f32 v[22:23], v[22:23], v[226:227], v[230:231]
	v_pk_fma_f32 v[24:25], v[16:17], v[228:229], v[232:233]
	v_cvt_pk_bf16_f32 v16, v18, v19
	v_cvt_pk_bf16_f32 v17, v20, v21
	v_cvt_pk_bf16_f32 v18, v22, v23
	v_cvt_pk_bf16_f32 v19, v24, v25
	ds_write_b128 v92, v[16:19]
	ds_read_b64 v[16:17], v93 offset:32768
	v_lshlrev_b32_e32 v20, 16, v43
	v_and_b32_e32 v21, 0xffff0000, v43
	v_lshlrev_b32_e32 v22, 16, v44
	v_and_b32_e32 v23, 0xffff0000, v44
	s_waitcnt lgkmcnt(0)
	v_pk_add_f32 v[18:19], v[26:27], v[16:17] op_sel_hi:[1,0] neg_lo:[0,1] neg_hi:[0,1]
	v_pk_add_f32 v[24:25], v[28:29], v[16:17] op_sel_hi:[1,0] neg_lo:[0,1] neg_hi:[0,1]
	v_pk_add_f32 v[26:27], v[30:31], v[16:17] op_sel_hi:[1,0] neg_lo:[0,1] neg_hi:[0,1]
	v_pk_add_f32 v[28:29], v[68:69], v[16:17] op_sel_hi:[1,0] neg_lo:[0,1] neg_hi:[0,1]
	v_pk_mul_f32 v[18:19], v[16:17], v[18:19] op_sel:[1,0]
	v_pk_mul_f32 v[24:25], v[16:17], v[24:25] op_sel:[1,0]
	v_pk_mul_f32 v[26:27], v[16:17], v[26:27] op_sel:[1,0]
	v_pk_mul_f32 v[16:17], v[16:17], v[28:29] op_sel:[1,0]
	v_pk_fma_f32 v[18:19], v[222:223], v[18:19], v[218:219]
	v_pk_fma_f32 v[24:25], v[224:225], v[24:25], v[220:221]
	v_pk_fma_f32 v[26:27], v[226:227], v[26:27], v[230:231]
	v_pk_fma_f32 v[28:29], v[228:229], v[16:17], v[232:233]
	v_cvt_pk_bf16_f32 v16, v18, v19
	v_cvt_pk_bf16_f32 v17, v24, v25
	v_cvt_pk_bf16_f32 v18, v26, v27
	v_cvt_pk_bf16_f32 v19, v28, v29
	ds_write_b128 v94, v[16:19]
	ds_read_b64 v[16:17], v95 offset:32768
	v_lshlrev_b32_e32 v24, 16, v45
	v_and_b32_e32 v25, 0xffff0000, v45
	v_lshlrev_b32_e32 v26, 16, v46
	v_and_b32_e32 v27, 0xffff0000, v46
	s_waitcnt lgkmcnt(0)
; #define LDSP(T, p) ((__attribute__((address_space(3))) T*)(p))
; DI unsigned pk2(float lo, float hi) { bf2_t v = __builtin_convertvector((f32x2){lo, hi}, bf2_t); return __builtin_bit_cast(unsigned, v); }
; DI void sg_phase(const Params& p, lds_t* shm) {
;     ...
;         o.x = pk2((bf_lo(v.x) - mu) * rs * g0[0] + b0[0], (bf_hi(v.x) - mu) * rs * g0[1] + b0[1]);
;         o.y = pk2((bf_lo(v.y) - mu) * rs * g0[2] + b0[2], (bf_hi(v.y) - mu) * rs * g0[3] + b0[3]);
;         o.z = pk2((bf_lo(v.z) - mu) * rs * g1[0] + b1[0], (bf_hi(v.z) - mu) * rs * g1[1] + b1[1]);
;         o.w = pk2((bf_lo(v.w) - mu) * rs * g1[2] + b1[2], (bf_hi(v.w) - mu) * rs * g1[3] + b1[3]);
;         *LDSP(u32x4, shm + off_a(row, ch)) = o;
;       }
;       if (g + 1 < 8) {
; #pragma unroll
;         for (int i = 0; i < 4; ++i) { const int idx = tid + 512 * i, row = idx >> 4, ch = idx & 15; raw[i] = *(const u32x4*)(Vs + (size_t)(w * 128 + row) * DM + (g + 1) * 128 + ch * 8); }
;       }
;       __syncthreads();
;       const int ib = wid & 3, chalf = wid >> 2, nks = (ib < 2) ? 4 : 8;
;       f32x16 acc[2];
; #pragma unroll
;       for (int cc = 0; cc < 2; ++cc)
; #pragma unroll
;         for (int i = 0; i < 16; ++i) acc[cc][i] = 0.f;
;       const bf16_t* wrow = wm + ((size_t)(g * 128 + ib * 32 + l31)) * 128 + 8 * h;
;       for (int ks = 0; ks < nks; ++ks) {
;         const bf16x8 bfr = *(const bf16x8*)(wrow + 16 * ks);
; #pragma unroll
;         for (int cc = 0; cc < 2; ++cc) {
;           const unsigned chb = 4 * (2 * chalf + cc) + 2 * blk + (pp >> 1);
;           const bf16x8 af = tr_pair(shm + off_a(16 * ks + 8 * h + q4, chb) + 8 * (pp & 1), shm + off_a(16 * ks + 8 * h + 4 + q4, chb) + 8 * (pp & 1));
;           acc[cc] = MFMA32(af, bfr, acc[cc]);
;         }
;       }
;       const int tok = w * 128 + ib * 32 + l31; const float bias = p.sg_b[g * 128 + ib * 32 + l31];
; #pragma unroll
;       for (int cc = 0; cc < 2; ++cc)
; #pragma unroll
;         for (int g4 = 0; g4 < 4; ++g4) {
;           bf16_t* up = U + (size_t)tok * DM + g * 128 + 32 * (2 * chalf + cc) + 8 * g4 + 4 * h;
;           const u32x2 uu = *(const u32x2*)up; f32x4 o;
;           o[0] = bf_lo(uu.x) * (acc[cc][4 * g4 + 0] + bias); o[1] = bf_hi(uu.x) * (acc[cc][4 * g4 + 1] + bias);
;           o[2] = bf_lo(uu.y) * (acc[cc][4 * g4 + 2] + bias); o[3] = bf_hi(uu.y) * (acc[cc][4 * g4 + 3] + bias);
;           st_bf4(up, o);
	v_pk_add_f32 v[18:19], v[100:101], v[16:17] op_sel_hi:[1,0] neg_lo:[0,1] neg_hi:[0,1]
	v_pk_add_f32 v[28:29], v[102:103], v[16:17] op_sel_hi:[1,0] neg_lo:[0,1] neg_hi:[0,1]
	v_pk_add_f32 v[30:31], v[104:105], v[16:17] op_sel_hi:[1,0] neg_lo:[0,1] neg_hi:[0,1]
	v_pk_add_f32 v[20:21], v[20:21], v[16:17] op_sel_hi:[1,0] neg_lo:[0,1] neg_hi:[0,1]
	v_pk_mul_f32 v[18:19], v[16:17], v[18:19] op_sel:[1,0]
	v_pk_mul_f32 v[28:29], v[16:17], v[28:29] op_sel:[1,0]
	v_pk_mul_f32 v[30:31], v[16:17], v[30:31] op_sel:[1,0]
	v_pk_mul_f32 v[16:17], v[16:17], v[20:21] op_sel:[1,0]
	v_pk_fma_f32 v[18:19], v[222:223], v[18:19], v[218:219]
	v_pk_fma_f32 v[20:21], v[224:225], v[28:29], v[220:221]
	v_pk_fma_f32 v[28:29], v[226:227], v[30:31], v[230:231]
	v_pk_fma_f32 v[30:31], v[228:229], v[16:17], v[232:233]
	v_cvt_pk_bf16_f32 v16, v18, v19
	v_cvt_pk_bf16_f32 v17, v20, v21
	v_cvt_pk_bf16_f32 v18, v28, v29
	v_cvt_pk_bf16_f32 v19, v30, v31
	ds_write_b128 v96, v[16:19]
	ds_read_b64 v[16:17], v97 offset:32768
	v_lshlrev_b32_e32 v18, 16, v47
	v_and_b32_e32 v19, 0xffff0000, v47
	s_waitcnt lgkmcnt(0)
	v_pk_add_f32 v[20:21], v[22:23], v[16:17] op_sel_hi:[1,0] neg_lo:[0,1] neg_hi:[0,1]
	v_pk_add_f32 v[22:23], v[24:25], v[16:17] op_sel_hi:[1,0] neg_lo:[0,1] neg_hi:[0,1]
	v_pk_add_f32 v[24:25], v[26:27], v[16:17] op_sel_hi:[1,0] neg_lo:[0,1] neg_hi:[0,1]
	v_pk_add_f32 v[18:19], v[18:19], v[16:17] op_sel_hi:[1,0] neg_lo:[0,1] neg_hi:[0,1]
	v_pk_mul_f32 v[20:21], v[16:17], v[20:21] op_sel:[1,0]
	v_pk_mul_f32 v[22:23], v[16:17], v[22:23] op_sel:[1,0]
	v_pk_mul_f32 v[24:25], v[16:17], v[24:25] op_sel:[1,0]
	v_pk_mul_f32 v[16:17], v[16:17], v[18:19] op_sel:[1,0]
	v_pk_fma_f32 v[0:1], v[222:223], v[20:21], v[218:219]
	v_pk_fma_f32 v[2:3], v[224:225], v[22:23], v[220:221]
	v_pk_fma_f32 v[4:5], v[226:227], v[24:25], v[230:231]
	v_pk_fma_f32 v[6:7], v[228:229], v[16:17], v[232:233]
	v_cvt_pk_bf16_f32 v0, v0, v1
	v_cvt_pk_bf16_f32 v1, v2, v3
	v_cvt_pk_bf16_f32 v2, v4, v5
	v_cvt_pk_bf16_f32 v3, v6, v7
	ds_write_b128 v98, v[0:3]
	v_or_b32_e32 v192, s1, v79
	v_mov_b32_e32 v193, 0
	v_lshl_add_u64 v[194:195], v[192:193], 2, s[46:47]
	v_lshlrev_b64 v[192:193], 8, v[192:193]
	v_lshl_add_u64 v[192:193], v[54:55], 0, v[192:193]
	global_load_dwordx4 v[160:163], v[192:193], off
	global_load_dwordx4 v[164:167], v[192:193], off offset:32
	global_load_dwordx4 v[168:171], v[192:193], off offset:64
	global_load_dwordx4 v[172:175], v[192:193], off offset:96
	global_load_dwordx4 v[176:179], v[192:193], off offset:128
	global_load_dwordx4 v[180:183], v[192:193], off offset:160
	global_load_dwordx4 v[184:187], v[192:193], off offset:192
	global_load_dwordx4 v[188:191], v[192:193], off offset:224
	global_load_dword v194, v[194:195], off
	s_lshl_b32 s8, s1, 1
	v_lshl_add_u64 v[130:131], v[66:67], 0, s[8:9]
	v_mbcnt_lo_u32_b32 v216, -1, 0
	v_mbcnt_hi_u32_b32 v216, -1, v216
	v_and_b32_e32 v216, 32, v216
	v_lshrrev_b32_e32 v216, 2, v216
	v_mov_b32_e32 v217, 0
	v_lshl_add_u64 v[130:131], v[130:131], 0, v[216:217]
	global_load_dwordx4 v[196:199], v[130:131], off
	global_load_dwordx4 v[200:203], v[130:131], off offset:32
	global_load_dwordx4 v[204:207], v[130:131], off offset:64
	global_load_dwordx4 v[208:211], v[130:131], off offset:96
	s_cmp_eq_u32 s4, 7
	s_cbranch_scc1 .Lsg_dummy
	s_lshl_b32 s8, s0, 8
	v_lshl_add_u64 v[0:1], v[52:53], 0, s[8:9]
	v_lshl_add_u64 v[2:3], v[0:1], 0, v[58:59]
	v_lshl_add_u64 v[4:5], v[0:1], 0, v[60:61]
	v_lshl_add_u64 v[6:7], v[0:1], 0, v[62:63]
	v_lshl_add_u64 v[0:1], v[0:1], 0, v[64:65]
	global_load_dwordx4 v[32:35], v[2:3], off
	global_load_dwordx4 v[36:39], v[4:5], off
	global_load_dwordx4 v[40:43], v[6:7], off
	global_load_dwordx4 v[44:47], v[0:1], off
	s_lshl_b32 s99, s0, 7
	v_or_b32_e32 v234, s99, v77
	v_mov_b32_e32 v235, 0
	v_lshlrev_b64 v[234:235], 2, v[234:235]
	v_lshl_add_u64 v[236:237], s[40:41], 0, v[234:235]
	v_lshl_add_u64 v[234:235], s[42:43], 0, v[234:235]
	global_load_dwordx4 v[218:221], v[234:235], off
	global_load_dwordx4 v[222:225], v[236:237], off
	global_load_dwordx4 v[226:229], v[236:237], off offset:16
	global_load_dwordx4 v[230:233], v[234:235], off offset:16
	s_branch .LBB0_398
.Lsg_dummy:
	global_load_dword v132, v[192:193], off
	global_load_dword v132, v[192:193], off
	global_load_dword v132, v[192:193], off
	global_load_dword v132, v[192:193], off
	global_load_dword v132, v[192:193], off
	global_load_dword v132, v[192:193], off
	global_load_dword v132, v[192:193], off
	global_load_dword v132, v[192:193], off

; DI float bf_lo(unsigned u) { return __uint_as_float(u << 16); }
; DI float bf_hi(unsigned u) { return __uint_as_float(u & 0xffff0000u); }
; DI void st_bf4(bf16_t* p, f32x4 v) { u32x2 w; w.x = pk2(v[0], v[1]); w.y = pk2(v[2], v[3]); *(u32x2*)p = w; }
; DI void sg_phase(const Params& p, lds_t* shm) {
;     ...
;       const int tok = w * 128 + ib * 32 + l31; const float bias = p.sg_b[g * 128 + ib * 32 + l31];
; #pragma unroll
;       for (int cc = 0; cc < 2; ++cc)
; #pragma unroll
;         for (int g4 = 0; g4 < 4; ++g4) {
;           bf16_t* up = U + (size_t)tok * DM + g * 128 + 32 * (2 * chalf + cc) + 8 * g4 + 4 * h;
;           const u32x2 uu = *(const u32x2*)up; f32x4 o;
;           o[0] = bf_lo(uu.x) * (acc[cc][4 * g4 + 0] + bias); o[1] = bf_hi(uu.x) * (acc[cc][4 * g4 + 1] + bias);
;           o[2] = bf_lo(uu.y) * (acc[cc][4 * g4 + 2] + bias); o[3] = bf_hi(uu.y) * (acc[cc][4 * g4 + 3] + bias);
;           st_bf4(up, o);
;         }
;     }
;   }
.Lsg_done:
	s_or_b64 exec, exec, s[6:7]
	s_lshl_b32 s8, s1, 1
	v_lshl_add_u64 v[68:69], v[66:67], 0, s[8:9]
	v_lshl_add_u64 v[68:69], v[68:69], 0, v[216:217]
	s_waitcnt vmcnt(12)
	s_nop 7
	s_nop 7
	v_pk_add_f32 v[16:17], v[16:17], v[194:195] op_sel_hi:[1,0]
	v_pk_add_f32 v[18:19], v[18:19], v[194:195] op_sel_hi:[1,0]
	v_pk_add_f32 v[20:21], v[20:21], v[194:195] op_sel_hi:[1,0]
	v_pk_add_f32 v[22:23], v[22:23], v[194:195] op_sel_hi:[1,0]
	v_pk_add_f32 v[24:25], v[24:25], v[194:195] op_sel_hi:[1,0]
	v_pk_add_f32 v[26:27], v[26:27], v[194:195] op_sel_hi:[1,0]
	v_pk_add_f32 v[28:29], v[28:29], v[194:195] op_sel_hi:[1,0]
	v_pk_add_f32 v[30:31], v[30:31], v[194:195] op_sel_hi:[1,0]
	v_pk_add_f32 v[0:1], v[0:1], v[194:195] op_sel_hi:[1,0]
	v_pk_add_f32 v[2:3], v[2:3], v[194:195] op_sel_hi:[1,0]
	v_pk_add_f32 v[4:5], v[4:5], v[194:195] op_sel_hi:[1,0]
	v_pk_add_f32 v[6:7], v[6:7], v[194:195] op_sel_hi:[1,0]
	v_pk_add_f32 v[8:9], v[8:9], v[194:195] op_sel_hi:[1,0]
	v_pk_add_f32 v[10:11], v[10:11], v[194:195] op_sel_hi:[1,0]
	v_pk_add_f32 v[12:13], v[12:13], v[194:195] op_sel_hi:[1,0]
	v_pk_add_f32 v[14:15], v[14:15], v[194:195] op_sel_hi:[1,0]
	s_nop 1
	v_permlane32_swap_b32_e32 v16, v20
	v_permlane32_swap_b32_e32 v17, v21
	v_permlane32_swap_b32_e32 v18, v22
	v_permlane32_swap_b32_e32 v19, v23
	v_permlane32_swap_b32_e32 v24, v28
	v_permlane32_swap_b32_e32 v25, v29
	v_permlane32_swap_b32_e32 v26, v30
	v_permlane32_swap_b32_e32 v27, v31
	v_permlane32_swap_b32_e32 v0, v4
	v_permlane32_swap_b32_e32 v1, v5
	v_permlane32_swap_b32_e32 v2, v6
	v_permlane32_swap_b32_e32 v3, v7
	v_permlane32_swap_b32_e32 v8, v12
	v_permlane32_swap_b32_e32 v9, v13
	v_permlane32_swap_b32_e32 v10, v14
	v_permlane32_swap_b32_e32 v11, v15
	s_waitcnt vmcnt(11)
	v_lshlrev_b32_e32 v100, 16, v196
	v_and_b32_e32 v101, 0xffff0000, v196
	v_lshlrev_b32_e32 v102, 16, v197
	v_and_b32_e32 v103, 0xffff0000, v197
	v_lshlrev_b32_e32 v104, 16, v198
	v_and_b32_e32 v105, 0xffff0000, v198
	v_lshlrev_b32_e32 v106, 16, v199
	v_and_b32_e32 v107, 0xffff0000, v199
	v_pk_mul_f32 v[16:17], v[16:17], v[100:101]
	v_pk_mul_f32 v[18:19], v[18:19], v[102:103]
	v_pk_mul_f32 v[20:21], v[20:21], v[104:105]
	v_pk_mul_f32 v[22:23], v[22:23], v[106:107]
	v_cvt_pk_bf16_f32 v16, v16, v17
	v_cvt_pk_bf16_f32 v17, v18, v19
	v_cvt_pk_bf16_f32 v18, v20, v21
	v_cvt_pk_bf16_f32 v19, v22, v23
	global_store_dwordx4 v[68:69], v[16:19], off
	s_waitcnt vmcnt(10)
	v_lshlrev_b32_e32 v108, 16, v200
	v_and_b32_e32 v109, 0xffff0000, v200
	v_lshlrev_b32_e32 v110, 16, v201
	v_and_b32_e32 v111, 0xffff0000, v201
	v_lshlrev_b32_e32 v112, 16, v202
	v_and_b32_e32 v113, 0xffff0000, v202
	v_lshlrev_b32_e32 v114, 16, v203
	v_and_b32_e32 v115, 0xffff0000, v203
	v_pk_mul_f32 v[24:25], v[24:25], v[108:109]
	v_pk_mul_f32 v[26:27], v[26:27], v[110:111]
	v_pk_mul_f32 v[28:29], v[28:29], v[112:113]
	v_pk_mul_f32 v[30:31], v[30:31], v[114:115]
	v_cvt_pk_bf16_f32 v24, v24, v25
	v_cvt_pk_bf16_f32 v25, v26, v27
	v_cvt_pk_bf16_f32 v26, v28, v29
	v_cvt_pk_bf16_f32 v27, v30, v31
	global_store_dwordx4 v[68:69], v[24:27], off offset:32
	s_waitcnt vmcnt(9)
	v_lshlrev_b32_e32 v100, 16, v204
	v_and_b32_e32 v101, 0xffff0000, v204
	v_lshlrev_b32_e32 v102, 16, v205
	v_and_b32_e32 v103, 0xffff0000, v205
	v_lshlrev_b32_e32 v104, 16, v206
	v_and_b32_e32 v105, 0xffff0000, v206
	v_lshlrev_b32_e32 v106, 16, v207
	v_and_b32_e32 v107, 0xffff0000, v207
	v_pk_mul_f32 v[0:1], v[0:1], v[100:101]
	v_pk_mul_f32 v[2:3], v[2:3], v[102:103]
	v_pk_mul_f32 v[4:5], v[4:5], v[104:105]
	v_pk_mul_f32 v[6:7], v[6:7], v[106:107]
	v_cvt_pk_bf16_f32 v0, v0, v1
	v_cvt_pk_bf16_f32 v1, v2, v3
	v_cvt_pk_bf16_f32 v2, v4, v5
	v_cvt_pk_bf16_f32 v3, v6, v7
	global_store_dwordx4 v[68:69], v[0:3], off offset:64
	s_waitcnt vmcnt(8)
	v_lshlrev_b32_e32 v108, 16, v208
	v_and_b32_e32 v109, 0xffff0000, v208
	v_lshlrev_b32_e32 v110, 16, v209
	v_and_b32_e32 v111, 0xffff0000, v209
	v_lshlrev_b32_e32 v112, 16, v210
	v_and_b32_e32 v113, 0xffff0000, v210
	v_lshlrev_b32_e32 v114, 16, v211
	v_and_b32_e32 v115, 0xffff0000, v211
	v_pk_mul_f32 v[8:9], v[8:9], v[108:109]
	v_pk_mul_f32 v[10:11], v[10:11], v[110:111]
	v_pk_mul_f32 v[12:13], v[12:13], v[112:113]
	v_pk_mul_f32 v[14:15], v[14:15], v[114:115]
	v_cvt_pk_bf16_f32 v8, v8, v9
	v_cvt_pk_bf16_f32 v9, v10, v11
	v_cvt_pk_bf16_f32 v10, v12, v13
	v_cvt_pk_bf16_f32 v11, v14, v15
	global_store_dwordx4 v[68:69], v[8:11], off offset:96
	s_cmp_eq_u32 s0, 8
	s_cbranch_scc0 .LBB0_396
	s_add_i32 s3, s3, s90
	s_cmpk_gt_i32 s3, 0xff
	s_cbranch_scc0 .LBB0_387
